# row-norm phases: the 64-lane butterfly sums on the register file (DPP for 1/2/4/8, v_permlane16/32_swap for 16/32) instead of six ds_bpermute round trips per row
# baseline (speedup 1.0000x reference)
; __device__ __forceinline__ unsigned cvt_pk_bf16(float lo, float hi) { unsigned r; asm volatile("v_cvt_pk_bf16_f32 %0, %1, %2" : "=v"(r) : "v"(lo), "v"(hi)); return r; }
; __device__ __forceinline__ float wave_sum(float v) {
; #pragma unroll
;     for (int o = 1; o < 64; o <<= 1) v += __shfl_xor(v, o);
;     return v;
; }
; __device__ __forceinline__ void p0_prologue(LAS unsigned char* lds, int G, int bid, int tid) {
;     ...
;         for (int m = gw; m < M; m += NGW) {
;             f32x4 v[4]; float s = 0.f;
; #pragma unroll
;             for (int j = 0; j < 4; ++j) { v[j] = nx[j]; s += (v[j].x * v[j].x + v[j].y * v[j].y) + (v[j].z * v[j].z + v[j].w * v[j].w); }
;             if (m + NGW < M) {
; #pragma unroll
;                 for (int j = 0; j < 4; ++j) nx[j] = *((const f32x4*)(xin + (size_t)(m + NGW) * D) + lane + 64 * j); }
;             const float rstd = 1.0f / sqrtf(wave_sum(s) * (1.0f / D) + 1e-6f);
;             u32x2* o8 = (u32x2*)(XN + (size_t)m * D) + lane;
; #pragma unroll
;             for (int j = 0; j < 4; ++j) { const f32x4 o = v[j] * rstd * gv[j]; u32x2 w; w.x = cvt_pk_bf16(o.x, o.y); w.y = cvt_pk_bf16(o.z, o.w); o8[64 * j] = w; }
;         }
.LBB0_79:
	v_mul_f32_e32 v64, v31, v31
	v_mul_f32_e32 v65, v33, v33
	v_fmac_f32_e32 v64, v30, v30
	v_fmac_f32_e32 v65, v32, v32
	v_add_f32_e32 v64, v64, v65
	v_mul_f32_e32 v65, v27, v27
	v_mul_f32_e32 v66, v29, v29
	v_fmac_f32_e32 v65, v26, v26
	v_fmac_f32_e32 v66, v28, v28
	v_add_f32_e32 v65, v65, v66
	v_add_f32_e32 v64, v64, v65
	v_mul_f32_e32 v65, v23, v23
	v_mul_f32_e32 v66, v25, v25
	v_fmac_f32_e32 v65, v22, v22
	v_fmac_f32_e32 v66, v24, v24
	v_add_f32_e32 v65, v65, v66
	v_add_f32_e32 v64, v65, v64
	v_mul_f32_e32 v65, v19, v19
	v_mul_f32_e32 v66, v21, v21
	v_fmac_f32_e32 v65, v18, v18
	v_fmac_f32_e32 v66, v20, v20
	v_add_f32_e32 v65, v65, v66
	v_add_f32_e32 v64, v65, v64
	s_nop 1
	v_mov_b32_dpp v65, v64 quad_perm:[1,0,3,2] row_mask:0xf bank_mask:0xf
	s_waitcnt lgkmcnt(0)
	v_add_f32_e32 v64, v64, v65
	s_nop 1
	v_mov_b32_dpp v65, v64 quad_perm:[2,3,0,1] row_mask:0xf bank_mask:0xf
	s_waitcnt lgkmcnt(0)
	v_add_f32_e32 v64, v64, v65
	s_nop 1
	v_mov_b32_dpp v65, v64 row_half_mirror row_mask:0xf bank_mask:0xf
	s_waitcnt lgkmcnt(0)
	v_add_f32_e32 v64, v64, v65
	s_nop 1
	v_mov_b32_dpp v65, v64 row_mirror row_mask:0xf bank_mask:0xf
	s_waitcnt lgkmcnt(0)
	v_add_f32_e32 v64, v64, v65
	v_mov_b32_e32 v65, v64
	s_nop 1
	v_permlane16_swap_b32_e32 v64, v65
	s_waitcnt lgkmcnt(0)
	v_add_f32_e32 v64, v64, v65
	v_mov_b32_e32 v65, v64
	s_nop 1
	v_permlane32_swap_b32_e32 v64, v65
	s_waitcnt lgkmcnt(0)
	v_add_f32_e32 v64, v64, v65
	v_fmamk_f32 v64, v64, 0x3a800000, v62
	v_mul_f32_e32 v65, 0x4f800000, v64
	v_cmp_gt_f32_e32 vcc, s13, v64
	s_nop 1
	v_cndmask_b32_e32 v64, v64, v65, vcc
	v_sqrt_f32_e32 v65, v64
	s_nop 0
	v_add_u32_e32 v66, -1, v65
	v_add_u32_e32 v67, 1, v65
	v_fma_f32 v68, -v66, v65, v64
	v_fma_f32 v69, -v67, v65, v64
	v_cmp_ge_f32_e64 s[2:3], 0, v68
	s_nop 1
	v_cndmask_b32_e64 v65, v65, v66, s[2:3]
	v_cmp_lt_f32_e64 s[2:3], 0, v69
	s_nop 1
	v_cndmask_b32_e64 v65, v65, v67, s[2:3]
	v_mul_f32_e32 v66, 0x37800000, v65
	v_cndmask_b32_e32 v65, v65, v66, vcc
	v_cmp_class_f32_e32 vcc, v64, v63
	s_nop 1
	v_cndmask_b32_e32 v64, v65, v64, vcc
	v_div_scale_f32 v65, s[2:3], v64, v64, 1.0
	v_rcp_f32_e32 v66, v65
	v_div_scale_f32 v67, vcc, 1.0, v64, 1.0
	v_fma_f32 v68, -v65, v66, 1.0
	v_fmac_f32_e32 v66, v68, v66
	v_mul_f32_e32 v68, v67, v66
	v_fma_f32 v69, -v65, v68, v67
	v_fmac_f32_e32 v68, v69, v66
	v_fma_f32 v65, -v65, v68, v67
	v_div_fmas_f32 v65, v65, v66, v68
	v_div_fixup_f32 v64, v65, v64, 1.0
	v_pk_mul_f32 v[30:31], v[30:31], v[64:65] op_sel_hi:[1,0]
	v_pk_mul_f32 v[26:27], v[26:27], v[64:65] op_sel_hi:[1,0]
	v_pk_mul_f32 v[22:23], v[22:23], v[64:65] op_sel_hi:[1,0]
	v_pk_mul_f32 v[18:19], v[18:19], v[64:65] op_sel_hi:[1,0]
	v_pk_mul_f32 v[32:33], v[32:33], v[64:65] op_sel_hi:[1,0]
	v_pk_mul_f32 v[30:31], v[2:3], v[30:31]
	v_pk_mul_f32 v[28:29], v[28:29], v[64:65] op_sel_hi:[1,0]
	v_pk_mul_f32 v[26:27], v[6:7], v[26:27]
	v_pk_mul_f32 v[24:25], v[24:25], v[64:65] op_sel_hi:[1,0]
	v_pk_mul_f32 v[22:23], v[10:11], v[22:23]
	v_pk_mul_f32 v[20:21], v[20:21], v[64:65] op_sel_hi:[1,0]
	v_pk_mul_f32 v[18:19], v[14:15], v[18:19]
	v_pk_mul_f32 v[32:33], v[4:5], v[32:33]
	v_cvt_pk_bf16_f32 v30, v30, v31
	v_pk_mul_f32 v[28:29], v[8:9], v[28:29]
	v_cvt_pk_bf16_f32 v31, v32, v33
	global_store_dwordx2 v[54:55], v[30:31], off offset:-1024
	v_cvt_pk_bf16_f32 v26, v26, v27
	v_cvt_pk_bf16_f32 v27, v28, v29
	global_store_dwordx2 v[54:55], v[26:27], off offset:-512
	v_pk_mul_f32 v[24:25], v[12:13], v[24:25]
	v_cvt_pk_bf16_f32 v22, v22, v23
	v_pk_mul_f32 v[20:21], v[16:17], v[20:21]
	v_cvt_pk_bf16_f32 v23, v24, v25
	global_store_dwordx2 v[54:55], v[22:23], off
	v_cvt_pk_bf16_f32 v18, v18, v19
	v_cvt_pk_bf16_f32 v19, v20, v21
	global_store_dwordx2 v[54:55], v[18:19], off offset:512
	v_lshl_add_u64 v[54:55], v[54:55], 0, s[0:1]
	s_and_b64 vcc, exec, s[16:17]
	s_waitcnt vmcnt(7)
	v_mov_b32_e32 v30, v34
	v_mov_b32_e32 v31, v35
	v_mov_b32_e32 v32, v36
	v_mov_b32_e32 v33, v37
	s_waitcnt vmcnt(6)
	v_mov_b32_e32 v26, v38
	v_mov_b32_e32 v27, v39
	v_mov_b32_e32 v28, v40
	v_mov_b32_e32 v29, v41
	s_waitcnt vmcnt(5)
	v_mov_b32_e32 v22, v42
	v_mov_b32_e32 v23, v43
	v_mov_b32_e32 v24, v44
	v_mov_b32_e32 v25, v45
	s_waitcnt vmcnt(4)
	v_mov_b32_e32 v18, v46
	v_mov_b32_e32 v19, v47
	v_mov_b32_e32 v20, v48
	v_mov_b32_e32 v21, v49
	s_cbranch_vccnz .LBB0_82

; __device__ __forceinline__ void unpack8(const u32x4 w, f32x4& a, f32x4& b) { a = (f32x4){bflo(w.x), bfhi(w.x), bflo(w.y), bfhi(w.y)}; b = (f32x4){bflo(w.z), bfhi(w.z), bflo(w.w), bfhi(w.w)}; }
; #define LERP_LOAD(mm) do { const bool hp_ = ((mm) & (T - 1)) != 0; _Pragma("unroll") for (int j = 0; j < 2; ++j) { const size_t off_ = (size_t)(mm) * D + j * 512 + lane * 8; \
;         rc_[j] = *(const u32x4*)(H1 + off_); rp_[j] = hp_ ? *(const u32x4*)(H1 + off_ - D) : (u32x4){0u, 0u, 0u, 0u}; } } while (0)
; __device__ __forceinline__ float wave_sum(float v) {
; #pragma unroll
;     for (int o = 1; o < 64; o <<= 1) v += __shfl_xor(v, o);
;     return v;
; }
; template <int ROUND>
; __device__ __forceinline__ void lerp_phase(const bf16_t* H1, const float* g1, const float* mu, bf16_t* HN, bf16_t* XS0, bf16_t* XS1, int G, int bid, int tid) {
;     ...
;     for (int m = gw; m < M; m += NGW) {
;         f32x4 c[4], p[4];
;         float sc = 0.f, sp = 0.f;
; #pragma unroll
;         for (int j = 0; j < 2; ++j) { unpack8(rc_[j], c[2 * j], c[2 * j + 1]); unpack8(rp_[j], p[2 * j], p[2 * j + 1]); }
;         if (m + NGW < M) LERP_LOAD(m + NGW);
; #pragma unroll
;         for (int q = 0; q < 4; ++q) { sc += (c[q].x * c[q].x + c[q].y * c[q].y) + (c[q].z * c[q].z + c[q].w * c[q].w); sp += (p[q].x * p[q].x + p[q].y * p[q].y) + (p[q].z * p[q].z + p[q].w * p[q].w); }
;         const float rc = 1.0f / sqrtf(wave_sum(sc) * (1.0f / D) + 1e-6f), rp = 1.0f / sqrtf(wave_sum(sp) * (1.0f / D) + 1e-6f);
.LBB0_461:
	v_lshlrev_b32_e32 v91, 16, v83
	v_lshlrev_b32_e32 v90, 16, v82
	v_and_b32_e32 v83, 0xffff0000, v83
	v_and_b32_e32 v82, 0xffff0000, v82
	v_pk_mul_f32 v[116:117], v[82:83], v[82:83]
	v_lshlrev_b32_e32 v96, 16, v80
	v_lshlrev_b32_e32 v98, 16, v81
	v_pk_fma_f32 v[116:117], v[90:91], v[90:91], v[116:117]
	v_and_b32_e32 v97, 0xffff0000, v80
	v_and_b32_e32 v99, 0xffff0000, v81
	v_lshlrev_b32_e32 v108, 16, v76
	v_and_b32_e32 v109, 0xffff0000, v76
	v_lshlrev_b32_e32 v76, 16, v72
	v_mul_f32_e32 v112, v96, v96
	v_mul_f32_e32 v114, v98, v98
	v_pk_add_f32 v[116:117], v[116:117], v[116:117] op_sel_hi:[0,1]
	v_lshlrev_b32_e32 v110, 16, v77
	v_and_b32_e32 v111, 0xffff0000, v77
	v_lshlrev_b32_e32 v92, 16, v78
	v_and_b32_e32 v94, 0xffff0000, v78
	v_and_b32_e32 v77, 0xffff0000, v72
	v_lshlrev_b32_e32 v78, 16, v73
	v_lshlrev_b32_e32 v68, 16, v74
	v_pk_fma_f32 v[112:113], v[96:97], v[96:97], v[112:113] op_sel_hi:[1,1,0]
	v_pk_fma_f32 v[114:115], v[98:99], v[98:99], v[114:115] op_sel_hi:[1,1,0]
	v_mul_f32_e32 v116, v76, v76
	v_lshlrev_b32_e32 v93, 16, v79
	v_and_b32_e32 v95, 0xffff0000, v79
	v_and_b32_e32 v79, 0xffff0000, v73
	v_lshlrev_b32_e32 v80, 16, v69
	v_and_b32_e32 v81, 0xffff0000, v69
	v_pk_fma_f32 v[118:119], v[76:77], v[76:77], v[116:117] op_sel_hi:[1,1,0]
	v_mul_f32_e32 v116, v78, v78
	v_mov_b32_e32 v69, v113
	v_mov_b32_e32 v122, v68
	v_mov_b32_e32 v123, v115
	v_and_b32_e32 v49, 0xffff0000, v74
	v_lshlrev_b32_e32 v72, 16, v75
	v_and_b32_e32 v73, 0xffff0000, v75
	v_pk_fma_f32 v[120:121], v[78:79], v[78:79], v[116:117] op_sel_hi:[1,1,0]
	v_pk_mul_f32 v[122:123], v[68:69], v[122:123]
	v_pk_add_f32 v[112:113], v[112:113], v[114:115]
	v_mul_f32_e32 v116, v49, v49
	v_mul_f32_e32 v118, v72, v72
	v_mul_f32_e32 v120, v73, v73
	v_mov_b32_e32 v123, v113
	v_pk_add_f32 v[112:113], v[122:123], v[116:117]
	v_pk_add_f32 v[114:115], v[118:119], v[120:121]
	v_lshlrev_b32_e32 v74, 16, v89
	v_pk_add_f32 v[112:113], v[112:113], v[114:115]
	v_and_b32_e32 v75, 0xffff0000, v89
	v_add_f32_e32 v69, v112, v113
	s_nop 1
	v_mov_b32_dpp v89, v69 quad_perm:[1,0,3,2] row_mask:0xf bank_mask:0xf
	v_pk_mul_f32 v[116:117], v[94:95], v[94:95]
	v_mul_f32_e32 v112, v108, v108
	v_pk_fma_f32 v[116:117], v[92:93], v[92:93], v[116:117]
	v_mul_f32_e32 v114, v110, v110
	s_waitcnt lgkmcnt(0)
	v_add_f32_e32 v69, v69, v89
	s_nop 1
	v_mov_b32_dpp v89, v69 quad_perm:[2,3,0,1] row_mask:0xf bank_mask:0xf
	v_pk_add_f32 v[116:117], v[116:117], v[116:117] op_sel_hi:[0,1]
	v_mul_f32_e32 v116, v74, v74
	v_pk_fma_f32 v[112:113], v[108:109], v[108:109], v[112:113] op_sel_hi:[1,1,0]
	v_pk_fma_f32 v[114:115], v[110:111], v[110:111], v[114:115] op_sel_hi:[1,1,0]
	s_waitcnt lgkmcnt(0)
	v_add_f32_e32 v69, v69, v89
	s_nop 1
	v_mov_b32_dpp v89, v69 row_half_mirror row_mask:0xf bank_mask:0xf
	v_pk_fma_f32 v[118:119], v[74:75], v[74:75], v[116:117] op_sel_hi:[1,1,0]
	v_mul_f32_e32 v116, v80, v80
	v_lshlrev_b32_e32 v50, 16, v70
	v_and_b32_e32 v51, 0xffff0000, v70
	v_lshlrev_b32_e32 v70, 16, v71
	v_and_b32_e32 v71, 0xffff0000, v71
	v_pk_fma_f32 v[120:121], v[80:81], v[80:81], v[116:117] op_sel_hi:[1,1,0]
	v_pk_add_f32 v[112:113], v[112:113], v[114:115]
	v_mul_f32_e32 v116, v51, v51
	v_mul_f32_e32 v118, v70, v70
	v_mul_f32_e32 v120, v71, v71
	v_mul_f32_e32 v122, v50, v50
	v_mov_b32_e32 v123, v113
	v_pk_add_f32 v[112:113], v[122:123], v[116:117]
	v_pk_add_f32 v[114:115], v[118:119], v[120:121]
	s_waitcnt lgkmcnt(0)
	v_add_f32_e32 v69, v69, v89
	v_pk_add_f32 v[112:113], v[112:113], v[114:115]
	s_nop 1
	v_mov_b32_dpp v89, v69 row_mirror row_mask:0xf bank_mask:0xf
	v_add_f32_e32 v107, v112, v113
	s_nop 1
	v_mov_b32_dpp v112, v107 quad_perm:[1,0,3,2] row_mask:0xf bank_mask:0xf
	v_mov_b32_e32 v120, v90
	v_mov_b32_e32 v121, v82
	s_waitcnt lgkmcnt(1)
	v_add_f32_e32 v69, v69, v89
	v_mov_b32_e32 v89, v69
	s_nop 1
	v_permlane16_swap_b32_e32 v69, v89
	s_waitcnt lgkmcnt(1)
	v_add_f32_e32 v107, v107, v112
	s_nop 1
	v_mov_b32_dpp v112, v107 quad_perm:[2,3,0,1] row_mask:0xf bank_mask:0xf
	v_mov_b32_e32 v82, v91
	v_mov_b32_e32 v90, v93
	s_waitcnt lgkmcnt(1)
	v_add_f32_e32 v69, v69, v89
	v_mov_b32_e32 v89, v69
	s_nop 1
	v_permlane32_swap_b32_e32 v69, v89
	s_waitcnt lgkmcnt(1)
	v_add_f32_e32 v107, v107, v112
	s_nop 1
	v_mov_b32_dpp v112, v107 row_half_mirror row_mask:0xf bank_mask:0xf
	v_mov_b32_e32 v91, v95
	v_mov_b32_e32 v93, v94
	s_waitcnt lgkmcnt(1)
	v_add_f32_e32 v69, v69, v89
	v_fmamk_f32 v69, v69, 0x3a800000, v105
	s_waitcnt lgkmcnt(0)
	v_add_f32_e32 v107, v107, v112
	v_mul_f32_e32 v89, 0x4f800000, v69
	v_cmp_gt_f32_e32 vcc, s9, v69
	s_nop 1
	v_mov_b32_dpp v112, v107 row_mirror row_mask:0xf bank_mask:0xf
	s_waitcnt lgkmcnt(0)
	v_add_f32_e32 v107, v107, v112
	v_cndmask_b32_e32 v69, v69, v89, vcc
	v_sqrt_f32_e32 v89, v69
	v_mov_b32_e32 v112, v107
	s_nop 1
	v_permlane16_swap_b32_e32 v107, v112
	v_add_u32_e32 v113, -1, v89
	v_fma_f32 v114, -v113, v89, v69
	v_cmp_ge_f32_e64 s[2:3], 0, v114
	v_add_u32_e32 v114, 1, v89
	s_waitcnt lgkmcnt(0)
	v_add_f32_e32 v107, v107, v112
	v_cndmask_b32_e64 v113, v89, v113, s[2:3]
	v_fma_f32 v89, -v114, v89, v69
	v_cmp_lt_f32_e64 s[2:3], 0, v89
	v_mov_b32_e32 v112, v107
	s_nop 1
	v_permlane32_swap_b32_e32 v107, v112
	s_waitcnt lgkmcnt(0)
; __device__ __forceinline__ u32x4 pack8(const f32x4 a, const f32x4 b) { u32x4 w; w.x = cvt_pk_bf16(a[0], a[1]); w.y = cvt_pk_bf16(a[2], a[3]); w.z = cvt_pk_bf16(b[0], b[1]); w.w = cvt_pk_bf16(b[2], b[3]); return w; }
; template <int ROUND>
; __device__ __forceinline__ void lerp_phase(const bf16_t* H1, const float* g1, const float* mu, bf16_t* HN, bf16_t* XS0, bf16_t* XS1, int G, int bid, int tid) {
;     ...
;         const float rc = 1.0f / sqrtf(wave_sum(sc) * (1.0f / D) + 1e-6f), rp = 1.0f / sqrtf(wave_sum(sp) * (1.0f / D) + 1e-6f);
; #pragma unroll
;         for (int j = 0; j < 2; ++j) {
;             const int col = j * 512 + lane * 8; const size_t off = (size_t)m * D + col;
;             f32x4 hn[2], xx[2], o0[2], o1[2];
; #pragma unroll
;             for (int e = 0; e < 2; ++e) {
;                 const f32x4 gv = gq[2 * j + e];
;                 hn[e] = c[2 * j + e] * rc * gv; xx[e] = p[2 * j + e] * rp * gv - hn[e];
;                 o0[e] = hn[e] + xx[e] * m0q[2 * j + e];
;                 o1[e] = hn[e] + xx[e] * m1q[2 * j + e];
;             }
;             if (ROUND == 0) *(u32x4*)(HN + off) = pack8(hn[0], hn[1]);
;             *(u32x4*)(XS0 + off) = pack8(o0[0], o0[1]);
;             *(u32x4*)(XS1 + off) = pack8(o1[0], o1[1]);
;         }
	v_add_f32_e32 v107, v107, v112
	v_cndmask_b32_e64 v89, v113, v114, s[2:3]
	v_mul_f32_e32 v113, 0x37800000, v89
	v_cndmask_b32_e32 v89, v89, v113, vcc
	v_cmp_class_f32_e32 vcc, v69, v106
	v_fmamk_f32 v107, v107, 0x3a800000, v105
	v_mul_f32_e32 v112, 0x4f800000, v107
	v_cndmask_b32_e32 v69, v89, v69, vcc
	v_div_scale_f32 v89, s[2:3], v69, v69, 1.0
	v_rcp_f32_e32 v113, v89
	v_cmp_gt_f32_e64 s[2:3], s9, v107
	v_fma_f32 v114, -v89, v113, 1.0
	s_nop 0
	v_cndmask_b32_e64 v107, v107, v112, s[2:3]
	v_fmac_f32_e32 v113, v114, v113
	v_div_scale_f32 v114, vcc, 1.0, v69, 1.0
	v_sqrt_f32_e32 v112, v107
	v_mul_f32_e32 v115, v114, v113
	v_fma_f32 v116, -v89, v115, v114
	v_fmac_f32_e32 v115, v116, v113
	v_fma_f32 v89, -v89, v115, v114
	v_add_u32_e32 v114, -1, v112
	v_fma_f32 v116, -v114, v112, v107
	v_cmp_ge_f32_e64 s[4:5], 0, v116
	v_add_u32_e32 v116, 1, v112
	v_div_fmas_f32 v89, v89, v113, v115
	v_cndmask_b32_e64 v114, v112, v114, s[4:5]
	v_fma_f32 v112, -v116, v112, v107
	v_cmp_lt_f32_e64 s[4:5], 0, v112
	s_nop 1
	v_cndmask_b32_e64 v112, v114, v116, s[4:5]
	v_mul_f32_e32 v114, 0x37800000, v112
	v_cndmask_b32_e64 v112, v112, v114, s[2:3]
	v_cmp_class_f32_e64 s[2:3], v107, v106
	s_nop 1
	v_cndmask_b32_e64 v107, v112, v107, s[2:3]
	v_div_scale_f32 v114, s[2:3], v107, v107, 1.0
	v_rcp_f32_e32 v116, v114
	v_div_fixup_f32 v112, v89, v69, 1.0
	v_fma_f32 v69, -v114, v116, 1.0
	v_fmac_f32_e32 v116, v69, v116
	v_div_scale_f32 v69, vcc, 1.0, v107, 1.0
	v_mul_f32_e32 v89, v69, v116
	v_fma_f32 v113, -v114, v89, v69
	v_fmac_f32_e32 v89, v113, v116
	v_fma_f32 v69, -v114, v89, v69
	v_div_fmas_f32 v69, v69, v116, v89
	v_div_fixup_f32 v114, v69, v107, 1.0
	v_pk_mul_f32 v[120:121], v[112:113], v[120:121] op_sel_hi:[0,1]
	v_pk_mul_f32 v[82:83], v[112:113], v[82:83] op_sel_hi:[0,1]
	v_pk_mul_f32 v[82:83], v[2:3], v[82:83]
	v_pk_mul_f32 v[120:121], v[0:1], v[120:121]
	v_pk_mul_f32 v[90:91], v[114:115], v[90:91] op_sel_hi:[0,1]
	v_pk_mul_f32 v[92:93], v[114:115], v[92:93] op_sel_hi:[0,1]
	v_pk_mul_f32 v[96:97], v[112:113], v[96:97] op_sel_hi:[0,1]
	v_pk_mul_f32 v[98:99], v[112:113], v[98:99] op_sel_hi:[0,1]
	v_pk_fma_f32 v[92:93], v[0:1], v[92:93], v[120:121] neg_lo:[0,0,1] neg_hi:[0,0,1]
	v_pk_fma_f32 v[90:91], v[2:3], v[90:91], v[82:83] neg_lo:[0,0,1] neg_hi:[0,0,1]
	v_pk_mul_f32 v[98:99], v[6:7], v[98:99]
	v_pk_mul_f32 v[96:97], v[4:5], v[96:97]
	v_pk_mul_f32 v[110:111], v[114:115], v[110:111] op_sel_hi:[0,1]
	v_pk_mul_f32 v[108:109], v[114:115], v[108:109] op_sel_hi:[0,1]
	v_pk_fma_f32 v[94:95], v[10:11], v[90:91], v[82:83]
	v_pk_fma_f32 v[122:123], v[8:9], v[92:93], v[120:121]
	v_pk_fma_f32 v[124:125], v[18:19], v[90:91], v[82:83]
	v_pk_fma_f32 v[126:127], v[16:17], v[92:93], v[120:121]
	v_cvt_pk_bf16_f32 v90, v96, v97
	v_cvt_pk_bf16_f32 v91, v98, v99
	v_cvt_pk_bf16_f32 v92, v120, v121
	v_cvt_pk_bf16_f32 v93, v82, v83
	v_add_co_u32_e32 v82, vcc, s14, v86
	v_mov_b32_e32 v69, v49
	v_pk_fma_f32 v[108:109], v[4:5], v[108:109], v[96:97] neg_lo:[0,0,1] neg_hi:[0,0,1]
	v_pk_fma_f32 v[110:111], v[6:7], v[110:111], v[98:99] neg_lo:[0,0,1] neg_hi:[0,0,1]
	v_addc_co_u32_e32 v83, vcc, -1, v87, vcc
	v_pk_mul_f32 v[68:69], v[68:69], v[112:113] op_sel_hi:[1,0]
	v_pk_mul_f32 v[72:73], v[72:73], v[112:113] op_sel_hi:[1,0]
	v_pk_fma_f32 v[116:117], v[14:15], v[110:111], v[98:99]
	v_pk_fma_f32 v[118:119], v[12:13], v[108:109], v[96:97]
	v_pk_fma_f32 v[108:109], v[20:21], v[108:109], v[96:97]
	global_store_dwordx4 v[82:83], v[90:93], off offset:-1024
	v_pk_mul_f32 v[76:77], v[112:113], v[76:77] op_sel_hi:[0,1]
	v_pk_mul_f32 v[78:79], v[112:113], v[78:79] op_sel_hi:[0,1]
	v_cvt_pk_bf16_f32 v90, v118, v119
	v_cvt_pk_bf16_f32 v91, v116, v117
	v_cvt_pk_bf16_f32 v92, v122, v123
	v_cvt_pk_bf16_f32 v93, v94, v95
	v_add_co_u32_e32 v94, vcc, s15, v86
	v_pk_mul_f32 v[72:73], v[26:27], v[72:73]
	v_pk_mul_f32 v[96:97], v[24:25], v[68:69]
	v_pk_mul_f32 v[68:69], v[114:115], v[70:71] op_sel_hi:[0,1]
	v_pk_fma_f32 v[110:111], v[22:23], v[110:111], v[98:99]
	v_addc_co_u32_e32 v95, vcc, -1, v87, vcc
	v_pk_mul_f32 v[78:79], v[30:31], v[78:79]
	v_pk_mul_f32 v[76:77], v[28:29], v[76:77]
	v_pk_mul_f32 v[80:81], v[114:115], v[80:81] op_sel_hi:[0,1]
	v_pk_mul_f32 v[74:75], v[114:115], v[74:75] op_sel_hi:[0,1]
	v_pk_mul_f32 v[50:51], v[114:115], v[50:51] op_sel_hi:[0,1]
	v_pk_fma_f32 v[68:69], v[26:27], v[68:69], v[72:73] neg_lo:[0,0,1] neg_hi:[0,0,1]
	global_store_dwordx4 v[94:95], v[90:93], off offset:-1024
	v_pk_fma_f32 v[74:75], v[28:29], v[74:75], v[76:77] neg_lo:[0,0,1] neg_hi:[0,0,1]
	v_pk_fma_f32 v[80:81], v[30:31], v[80:81], v[78:79] neg_lo:[0,0,1] neg_hi:[0,0,1]
	v_cvt_pk_bf16_f32 v90, v108, v109
	v_cvt_pk_bf16_f32 v91, v110, v111
	v_cvt_pk_bf16_f32 v92, v126, v127
	v_cvt_pk_bf16_f32 v93, v124, v125
	global_store_dwordx4 v[86:87], v[90:93], off offset:-1024
	v_pk_fma_f32 v[50:51], v[24:25], v[50:51], v[96:97] neg_lo:[0,0,1] neg_hi:[0,0,1]
	v_pk_fma_f32 v[98:99], v[34:35], v[68:69], v[72:73]
	v_pk_fma_f32 v[110:111], v[42:43], v[68:69], v[72:73]
	v_cvt_pk_bf16_f32 v68, v76, v77
	v_cvt_pk_bf16_f32 v69, v78, v79
	v_cvt_pk_bf16_f32 v70, v96, v97
	v_cvt_pk_bf16_f32 v71, v72, v73
	v_pk_fma_f32 v[90:91], v[38:39], v[80:81], v[78:79]
	v_pk_fma_f32 v[92:93], v[36:37], v[74:75], v[76:77]
	v_pk_fma_f32 v[80:81], v[46:47], v[80:81], v[78:79]
	v_pk_fma_f32 v[74:75], v[44:45], v[74:75], v[76:77]
	v_pk_fma_f32 v[108:109], v[32:33], v[50:51], v[96:97]
	global_store_dwordx4 v[82:83], v[68:71], off
	v_pk_fma_f32 v[50:51], v[40:41], v[50:51], v[96:97]
	s_waitcnt vmcnt(5)
	v_mov_b64_e32 v[78:79], v[58:59]
	v_cvt_pk_bf16_f32 v68, v92, v93
	v_cvt_pk_bf16_f32 v69, v90, v91
	v_cvt_pk_bf16_f32 v70, v108, v109
	v_cvt_pk_bf16_f32 v71, v98, v99
	global_store_dwordx4 v[94:95], v[68:71], off
	s_andn2_b64 vcc, exec, s[12:13]
	v_mov_b64_e32 v[76:77], v[56:57]
	v_cvt_pk_bf16_f32 v68, v74, v75
	v_cvt_pk_bf16_f32 v69, v80, v81
	v_cvt_pk_bf16_f32 v70, v50, v51
	v_cvt_pk_bf16_f32 v71, v110, v111
	v_mov_b64_e32 v[82:83], v[54:55]
	s_waitcnt vmcnt(5)
	v_mov_b64_e32 v[74:75], v[62:63]
	global_store_dwordx4 v[86:87], v[68:71], off
	v_lshl_add_u64 v[86:87], v[86:87], 0, s[10:11]
	v_mov_b64_e32 v[80:81], v[52:53]
	v_mov_b64_e32 v[72:73], v[60:61]
	v_mov_b32_e32 v89, v64
	v_mov_b32_e32 v69, v65
	v_mov_b32_e32 v70, v66
	v_mov_b32_e32 v71, v67
	s_cbranch_vccz .LBB0_467

; __device__ __forceinline__ void unpack8(const u32x4 w, f32x4& a, f32x4& b) { a = (f32x4){bflo(w.x), bfhi(w.x), bflo(w.y), bfhi(w.y)}; b = (f32x4){bflo(w.z), bfhi(w.z), bflo(w.w), bfhi(w.w)}; }
; #define LERP_LOAD(mm) do { const bool hp_ = ((mm) & (T - 1)) != 0; _Pragma("unroll") for (int j = 0; j < 2; ++j) { const size_t off_ = (size_t)(mm) * D + j * 512 + lane * 8; \
;         rc_[j] = *(const u32x4*)(H1 + off_); rp_[j] = hp_ ? *(const u32x4*)(H1 + off_ - D) : (u32x4){0u, 0u, 0u, 0u}; } } while (0)
; __device__ __forceinline__ float wave_sum(float v) {
; #pragma unroll
;     for (int o = 1; o < 64; o <<= 1) v += __shfl_xor(v, o);
;     return v;
; }
; template <int ROUND>
; __device__ __forceinline__ void lerp_phase(const bf16_t* H1, const float* g1, const float* mu, bf16_t* HN, bf16_t* XS0, bf16_t* XS1, int G, int bid, int tid) {
;     ...
;     for (int m = gw; m < M; m += NGW) {
;         f32x4 c[4], p[4];
;         float sc = 0.f, sp = 0.f;
; #pragma unroll
;         for (int j = 0; j < 2; ++j) { unpack8(rc_[j], c[2 * j], c[2 * j + 1]); unpack8(rp_[j], p[2 * j], p[2 * j + 1]); }
;         if (m + NGW < M) LERP_LOAD(m + NGW);
; #pragma unroll
;         for (int q = 0; q < 4; ++q) { sc += (c[q].x * c[q].x + c[q].y * c[q].y) + (c[q].z * c[q].z + c[q].w * c[q].w); sp += (p[q].x * p[q].x + p[q].y * p[q].y) + (p[q].z * p[q].z + p[q].w * p[q].w); }
;         const float rc = 1.0f / sqrtf(wave_sum(sc) * (1.0f / D) + 1e-6f), rp = 1.0f / sqrtf(wave_sum(sp) * (1.0f / D) + 1e-6f);
.LBB0_625:
	v_lshlrev_b32_e32 v91, 16, v83
	v_lshlrev_b32_e32 v90, 16, v82
	v_and_b32_e32 v83, 0xffff0000, v83
	v_and_b32_e32 v82, 0xffff0000, v82
	v_pk_mul_f32 v[118:119], v[82:83], v[82:83]
	v_lshlrev_b32_e32 v96, 16, v80
	v_lshlrev_b32_e32 v98, 16, v81
	v_pk_fma_f32 v[118:119], v[90:91], v[90:91], v[118:119]
	v_and_b32_e32 v97, 0xffff0000, v80
	v_and_b32_e32 v99, 0xffff0000, v81
	v_lshlrev_b32_e32 v110, 16, v76
	v_and_b32_e32 v111, 0xffff0000, v76
	v_lshlrev_b32_e32 v76, 16, v72
	v_mul_f32_e32 v114, v96, v96
	v_mul_f32_e32 v116, v98, v98
	v_pk_add_f32 v[118:119], v[118:119], v[118:119] op_sel_hi:[0,1]
	v_lshlrev_b32_e32 v112, 16, v77
	v_and_b32_e32 v113, 0xffff0000, v77
	v_lshlrev_b32_e32 v92, 16, v78
	v_and_b32_e32 v94, 0xffff0000, v78
	v_and_b32_e32 v77, 0xffff0000, v72
	v_lshlrev_b32_e32 v78, 16, v73
	v_lshlrev_b32_e32 v68, 16, v74
	v_pk_fma_f32 v[114:115], v[96:97], v[96:97], v[114:115] op_sel_hi:[1,1,0]
	v_pk_fma_f32 v[116:117], v[98:99], v[98:99], v[116:117] op_sel_hi:[1,1,0]
	v_mul_f32_e32 v118, v76, v76
	v_lshlrev_b32_e32 v93, 16, v79
	v_and_b32_e32 v95, 0xffff0000, v79
	v_and_b32_e32 v79, 0xffff0000, v73
	v_lshlrev_b32_e32 v80, 16, v69
	v_and_b32_e32 v81, 0xffff0000, v69
	v_pk_fma_f32 v[120:121], v[76:77], v[76:77], v[118:119] op_sel_hi:[1,1,0]
	v_mul_f32_e32 v118, v78, v78
	v_mov_b32_e32 v69, v115
	v_mov_b32_e32 v124, v68
	v_mov_b32_e32 v125, v117
	v_and_b32_e32 v49, 0xffff0000, v74
	v_lshlrev_b32_e32 v72, 16, v75
	v_and_b32_e32 v73, 0xffff0000, v75
	v_pk_fma_f32 v[122:123], v[78:79], v[78:79], v[118:119] op_sel_hi:[1,1,0]
	v_pk_mul_f32 v[124:125], v[68:69], v[124:125]
	v_pk_add_f32 v[114:115], v[114:115], v[116:117]
	v_mul_f32_e32 v118, v49, v49
	v_mul_f32_e32 v120, v72, v72
	v_mul_f32_e32 v122, v73, v73
	v_mov_b32_e32 v125, v115
	v_pk_add_f32 v[114:115], v[124:125], v[118:119]
	v_pk_add_f32 v[116:117], v[120:121], v[122:123]
	v_lshlrev_b32_e32 v74, 16, v89
	v_pk_add_f32 v[114:115], v[114:115], v[116:117]
	v_and_b32_e32 v75, 0xffff0000, v89
	v_add_f32_e32 v69, v114, v115
	s_nop 1
	v_mov_b32_dpp v89, v69 quad_perm:[1,0,3,2] row_mask:0xf bank_mask:0xf
	v_pk_mul_f32 v[118:119], v[94:95], v[94:95]
	v_mul_f32_e32 v114, v110, v110
	v_pk_fma_f32 v[118:119], v[92:93], v[92:93], v[118:119]
	v_mul_f32_e32 v116, v112, v112
	s_waitcnt lgkmcnt(0)
	v_add_f32_e32 v69, v69, v89
	s_nop 1
	v_mov_b32_dpp v89, v69 quad_perm:[2,3,0,1] row_mask:0xf bank_mask:0xf
	v_pk_add_f32 v[118:119], v[118:119], v[118:119] op_sel_hi:[0,1]
	v_mul_f32_e32 v118, v74, v74
	v_pk_fma_f32 v[114:115], v[110:111], v[110:111], v[114:115] op_sel_hi:[1,1,0]
	v_pk_fma_f32 v[116:117], v[112:113], v[112:113], v[116:117] op_sel_hi:[1,1,0]
	s_waitcnt lgkmcnt(0)
	v_add_f32_e32 v69, v69, v89
	s_nop 1
	v_mov_b32_dpp v89, v69 row_half_mirror row_mask:0xf bank_mask:0xf
	v_pk_fma_f32 v[120:121], v[74:75], v[74:75], v[118:119] op_sel_hi:[1,1,0]
	v_mul_f32_e32 v118, v80, v80
	v_lshlrev_b32_e32 v50, 16, v70
	v_and_b32_e32 v51, 0xffff0000, v70
	v_lshlrev_b32_e32 v70, 16, v71
	v_and_b32_e32 v71, 0xffff0000, v71
	v_pk_fma_f32 v[122:123], v[80:81], v[80:81], v[118:119] op_sel_hi:[1,1,0]
	v_pk_add_f32 v[114:115], v[114:115], v[116:117]
	v_mul_f32_e32 v118, v51, v51
	v_mul_f32_e32 v120, v70, v70
	v_mul_f32_e32 v122, v71, v71
	v_mul_f32_e32 v124, v50, v50
	v_mov_b32_e32 v125, v115
	v_pk_add_f32 v[114:115], v[124:125], v[118:119]
	v_pk_add_f32 v[116:117], v[120:121], v[122:123]
	s_waitcnt lgkmcnt(0)
	v_add_f32_e32 v69, v69, v89
	v_pk_add_f32 v[114:115], v[114:115], v[116:117]
	s_nop 1
	v_mov_b32_dpp v89, v69 row_mirror row_mask:0xf bank_mask:0xf
	v_add_f32_e32 v109, v114, v115
	s_nop 1
	v_mov_b32_dpp v114, v109 quad_perm:[1,0,3,2] row_mask:0xf bank_mask:0xf
	s_waitcnt lgkmcnt(1)
	v_add_f32_e32 v69, v69, v89
	v_mov_b32_e32 v89, v69
	s_nop 1
	v_permlane16_swap_b32_e32 v69, v89
	s_waitcnt lgkmcnt(1)
	v_add_f32_e32 v109, v109, v114
	s_nop 1
	v_mov_b32_dpp v114, v109 quad_perm:[2,3,0,1] row_mask:0xf bank_mask:0xf
	s_waitcnt lgkmcnt(1)
	v_add_f32_e32 v69, v69, v89
	v_mov_b32_e32 v89, v69
	s_nop 1
	v_permlane32_swap_b32_e32 v69, v89
	s_waitcnt lgkmcnt(1)
	v_add_f32_e32 v109, v109, v114
	s_nop 1
	v_mov_b32_dpp v114, v109 row_half_mirror row_mask:0xf bank_mask:0xf
	s_waitcnt lgkmcnt(1)
	v_add_f32_e32 v69, v69, v89
	v_fmamk_f32 v69, v69, 0x3a800000, v107
	s_waitcnt lgkmcnt(0)
	v_add_f32_e32 v109, v109, v114
	v_mul_f32_e32 v89, 0x4f800000, v69
	v_cmp_gt_f32_e32 vcc, s11, v69
	s_nop 1
	v_mov_b32_dpp v114, v109 row_mirror row_mask:0xf bank_mask:0xf
	s_waitcnt lgkmcnt(0)
	v_add_f32_e32 v109, v109, v114
	v_cndmask_b32_e32 v69, v69, v89, vcc
	v_sqrt_f32_e32 v89, v69
	v_mov_b32_e32 v114, v109
	s_nop 1
	v_permlane16_swap_b32_e32 v109, v114
	v_add_u32_e32 v115, -1, v89
	v_fma_f32 v116, -v115, v89, v69
	v_cmp_ge_f32_e64 s[2:3], 0, v116
	v_add_u32_e32 v116, 1, v89
	s_waitcnt lgkmcnt(0)
	v_add_f32_e32 v109, v109, v114
	v_cndmask_b32_e64 v115, v89, v115, s[2:3]
	v_fma_f32 v89, -v116, v89, v69
	v_cmp_lt_f32_e64 s[2:3], 0, v89
	v_mov_b32_e32 v114, v109
	s_nop 1
	v_permlane32_swap_b32_e32 v109, v114
	s_waitcnt lgkmcnt(0)
; __device__ __forceinline__ u32x4 pack8(const f32x4 a, const f32x4 b) { u32x4 w; w.x = cvt_pk_bf16(a[0], a[1]); w.y = cvt_pk_bf16(a[2], a[3]); w.z = cvt_pk_bf16(b[0], b[1]); w.w = cvt_pk_bf16(b[2], b[3]); return w; }
; template <int ROUND>
; __device__ __forceinline__ void lerp_phase(const bf16_t* H1, const float* g1, const float* mu, bf16_t* HN, bf16_t* XS0, bf16_t* XS1, int G, int bid, int tid) {
;     ...
;         const float rc = 1.0f / sqrtf(wave_sum(sc) * (1.0f / D) + 1e-6f), rp = 1.0f / sqrtf(wave_sum(sp) * (1.0f / D) + 1e-6f);
; #pragma unroll
;         for (int j = 0; j < 2; ++j) {
;             const int col = j * 512 + lane * 8; const size_t off = (size_t)m * D + col;
;             f32x4 hn[2], xx[2], o0[2], o1[2];
; #pragma unroll
;             for (int e = 0; e < 2; ++e) {
;                 const f32x4 gv = gq[2 * j + e];
;                 hn[e] = c[2 * j + e] * rc * gv; xx[e] = p[2 * j + e] * rp * gv - hn[e];
;                 o0[e] = hn[e] + xx[e] * m0q[2 * j + e];
;                 o1[e] = hn[e] + xx[e] * m1q[2 * j + e];
;             }
;             if (ROUND == 0) *(u32x4*)(HN + off) = pack8(hn[0], hn[1]);
;             *(u32x4*)(XS0 + off) = pack8(o0[0], o0[1]);
;             *(u32x4*)(XS1 + off) = pack8(o1[0], o1[1]);
;         }
	v_add_f32_e32 v109, v109, v114
	v_cndmask_b32_e64 v89, v115, v116, s[2:3]
	v_mul_f32_e32 v115, 0x37800000, v89
	v_cndmask_b32_e32 v89, v89, v115, vcc
	v_cmp_class_f32_e32 vcc, v69, v108
	v_fmamk_f32 v109, v109, 0x3a800000, v107
	v_mul_f32_e32 v114, 0x4f800000, v109
	v_cndmask_b32_e32 v69, v89, v69, vcc
	v_div_scale_f32 v89, s[2:3], v69, v69, 1.0
	v_rcp_f32_e32 v115, v89
	v_cmp_gt_f32_e64 s[2:3], s11, v109
	v_fma_f32 v116, -v89, v115, 1.0
	s_nop 0
	v_cndmask_b32_e64 v109, v109, v114, s[2:3]
	v_fmac_f32_e32 v115, v116, v115
	v_div_scale_f32 v116, vcc, 1.0, v69, 1.0
	v_sqrt_f32_e32 v114, v109
	v_mul_f32_e32 v117, v116, v115
	v_fma_f32 v118, -v89, v117, v116
	v_fmac_f32_e32 v117, v118, v115
	v_fma_f32 v89, -v89, v117, v116
	v_add_u32_e32 v116, -1, v114
	v_fma_f32 v118, -v116, v114, v109
	v_cmp_ge_f32_e64 s[4:5], 0, v118
	v_add_u32_e32 v118, 1, v114
	v_div_fmas_f32 v89, v89, v115, v117
	v_cndmask_b32_e64 v116, v114, v116, s[4:5]
	v_fma_f32 v114, -v118, v114, v109
	v_cmp_lt_f32_e64 s[4:5], 0, v114
	s_nop 1
	v_cndmask_b32_e64 v114, v116, v118, s[4:5]
	v_mul_f32_e32 v116, 0x37800000, v114
	v_cndmask_b32_e64 v114, v114, v116, s[2:3]
	v_cmp_class_f32_e64 s[2:3], v109, v108
	s_nop 1
	v_cndmask_b32_e64 v109, v114, v109, s[2:3]
	v_div_scale_f32 v116, s[2:3], v109, v109, 1.0
	v_rcp_f32_e32 v118, v116
	v_div_fixup_f32 v114, v89, v69, 1.0
	v_fma_f32 v69, -v116, v118, 1.0
	v_fmac_f32_e32 v118, v69, v118
	v_div_scale_f32 v69, vcc, 1.0, v109, 1.0
	v_mul_f32_e32 v89, v69, v118
	v_fma_f32 v115, -v116, v89, v69
	v_fmac_f32_e32 v89, v115, v118
	v_fma_f32 v69, -v116, v89, v69
	v_div_fmas_f32 v69, v69, v118, v89
	v_div_fixup_f32 v116, v69, v109, 1.0
	v_pk_mul_f32 v[96:97], v[114:115], v[96:97] op_sel_hi:[0,1]
	v_pk_mul_f32 v[96:97], v[4:5], v[96:97]
	v_pk_mul_f32 v[110:111], v[116:117], v[110:111] op_sel_hi:[0,1]
	v_pk_fma_f32 v[110:111], v[4:5], v[110:111], v[96:97] neg_lo:[0,0,1] neg_hi:[0,0,1]
	v_pk_mul_f32 v[98:99], v[114:115], v[98:99] op_sel_hi:[0,1]
	v_pk_fma_f32 v[120:121], v[12:13], v[110:111], v[96:97]
	v_pk_fma_f32 v[96:97], v[20:21], v[110:111], v[96:97]
	v_mov_b32_e32 v110, v90
	v_mov_b32_e32 v111, v82
	v_pk_mul_f32 v[110:111], v[114:115], v[110:111] op_sel_hi:[0,1]
	v_mov_b32_e32 v82, v91
	v_pk_mul_f32 v[82:83], v[114:115], v[82:83] op_sel_hi:[0,1]
	v_pk_mul_f32 v[90:91], v[0:1], v[110:111]
	v_mov_b32_e32 v110, v93
	v_mov_b32_e32 v111, v95
	v_pk_mul_f32 v[82:83], v[2:3], v[82:83]
	v_pk_mul_f32 v[110:111], v[116:117], v[110:111] op_sel_hi:[0,1]
	v_mov_b32_e32 v93, v94
	v_pk_mul_f32 v[98:99], v[6:7], v[98:99]
	v_pk_mul_f32 v[112:113], v[116:117], v[112:113] op_sel_hi:[0,1]
	v_pk_mul_f32 v[92:93], v[116:117], v[92:93] op_sel_hi:[0,1]
	v_pk_fma_f32 v[94:95], v[2:3], v[110:111], v[82:83] neg_lo:[0,0,1] neg_hi:[0,0,1]
	v_pk_fma_f32 v[112:113], v[6:7], v[112:113], v[98:99] neg_lo:[0,0,1] neg_hi:[0,0,1]
	v_pk_fma_f32 v[92:93], v[0:1], v[92:93], v[90:91] neg_lo:[0,0,1] neg_hi:[0,0,1]
	v_pk_fma_f32 v[110:111], v[10:11], v[94:95], v[82:83]
	v_mov_b32_e32 v69, v49
	v_pk_fma_f32 v[118:119], v[14:15], v[112:113], v[98:99]
	v_pk_fma_f32 v[98:99], v[22:23], v[112:113], v[98:99]
	v_pk_fma_f32 v[112:113], v[8:9], v[92:93], v[90:91]
	v_pk_fma_f32 v[82:83], v[18:19], v[94:95], v[82:83]
	v_pk_fma_f32 v[94:95], v[16:17], v[92:93], v[90:91]
	v_cvt_pk_bf16_f32 v90, v120, v121
	v_cvt_pk_bf16_f32 v91, v118, v119
	v_cvt_pk_bf16_f32 v92, v112, v113
	v_cvt_pk_bf16_f32 v93, v110, v111
	v_add_co_u32_e32 v110, vcc, s16, v86
	v_pk_mul_f32 v[76:77], v[114:115], v[76:77] op_sel_hi:[0,1]
	v_pk_mul_f32 v[78:79], v[114:115], v[78:79] op_sel_hi:[0,1]
	v_pk_mul_f32 v[68:69], v[68:69], v[114:115] op_sel_hi:[1,0]
	v_pk_mul_f32 v[72:73], v[72:73], v[114:115] op_sel_hi:[1,0]
	v_addc_co_u32_e32 v111, vcc, -1, v87, vcc
	v_pk_mul_f32 v[78:79], v[30:31], v[78:79]
	v_pk_mul_f32 v[76:77], v[28:29], v[76:77]
	v_pk_mul_f32 v[80:81], v[116:117], v[80:81] op_sel_hi:[0,1]
	v_pk_mul_f32 v[74:75], v[116:117], v[74:75] op_sel_hi:[0,1]
	v_pk_mul_f32 v[72:73], v[26:27], v[72:73]
	v_pk_mul_f32 v[68:69], v[24:25], v[68:69]
	v_pk_mul_f32 v[70:71], v[116:117], v[70:71] op_sel_hi:[0,1]
	v_pk_mul_f32 v[50:51], v[116:117], v[50:51] op_sel_hi:[0,1]
	global_store_dwordx4 v[110:111], v[90:93], off offset:-1024
	v_pk_fma_f32 v[74:75], v[28:29], v[74:75], v[76:77] neg_lo:[0,0,1] neg_hi:[0,0,1]
	v_pk_fma_f32 v[80:81], v[30:31], v[80:81], v[78:79] neg_lo:[0,0,1] neg_hi:[0,0,1]
	v_cvt_pk_bf16_f32 v90, v96, v97
	v_cvt_pk_bf16_f32 v91, v98, v99
	v_pk_fma_f32 v[50:51], v[24:25], v[50:51], v[68:69] neg_lo:[0,0,1] neg_hi:[0,0,1]
	v_pk_fma_f32 v[70:71], v[26:27], v[70:71], v[72:73] neg_lo:[0,0,1] neg_hi:[0,0,1]
	v_cvt_pk_bf16_f32 v92, v94, v95
	v_cvt_pk_bf16_f32 v93, v82, v83
	global_store_dwordx4 v[86:87], v[90:93], off offset:-1024
	v_pk_fma_f32 v[82:83], v[38:39], v[80:81], v[78:79]
	v_pk_fma_f32 v[78:79], v[46:47], v[80:81], v[78:79]
	v_pk_fma_f32 v[90:91], v[36:37], v[74:75], v[76:77]
	v_pk_fma_f32 v[74:75], v[44:45], v[74:75], v[76:77]
	v_pk_fma_f32 v[76:77], v[34:35], v[70:71], v[72:73]
	v_pk_fma_f32 v[80:81], v[32:33], v[50:51], v[68:69]
	v_pk_fma_f32 v[72:73], v[42:43], v[70:71], v[72:73]
	v_pk_fma_f32 v[50:51], v[40:41], v[50:51], v[68:69]
	v_cvt_pk_bf16_f32 v68, v90, v91
	v_cvt_pk_bf16_f32 v69, v82, v83
	v_cvt_pk_bf16_f32 v70, v80, v81
	v_cvt_pk_bf16_f32 v71, v76, v77
	global_store_dwordx4 v[110:111], v[68:71], off
	s_waitcnt vmcnt(4)
	v_mov_b64_e32 v[82:83], v[54:55]
	s_andn2_b64 vcc, exec, s[14:15]
	v_cvt_pk_bf16_f32 v68, v74, v75
	v_cvt_pk_bf16_f32 v69, v78, v79
	v_cvt_pk_bf16_f32 v70, v50, v51
	v_cvt_pk_bf16_f32 v71, v72, v73
	v_mov_b64_e32 v[78:79], v[58:59]
	s_waitcnt vmcnt(3)
	v_mov_b64_e32 v[74:75], v[62:63]
	global_store_dwordx4 v[86:87], v[68:71], off
	v_lshl_add_u64 v[86:87], v[86:87], 0, s[12:13]
	v_mov_b64_e32 v[76:77], v[56:57]
	v_mov_b64_e32 v[80:81], v[52:53]
	v_mov_b64_e32 v[72:73], v[60:61]
	v_mov_b32_e32 v89, v64
	v_mov_b32_e32 v69, v65
	v_mov_b32_e32 v70, v66
	v_mov_b32_e32 v71, v67
	s_cbranch_vccz .LBB0_631

; __device__ __forceinline__ void unpack8(const u32x4 w, f32x4& a, f32x4& b) { a = (f32x4){bflo(w.x), bfhi(w.x), bflo(w.y), bfhi(w.y)}; b = (f32x4){bflo(w.z), bfhi(w.z), bflo(w.w), bfhi(w.w)}; }
; __device__ __forceinline__ float wave_sum(float v) {
; #pragma unroll
;     for (int o = 1; o < 64; o <<= 1) v += __shfl_xor(v, o);
;     return v;
; }
; __device__ __forceinline__ void final_norm_phase(const bf16_t* H2, float* out, const float* g, int G, int bid, int tid) {
;     ...
;     for (int m = gw; m < M; m += NGW) {
;         f32x4 v[4]; float s = 0.f;
;         unpack8(rh_[0], v[0], v[1]); unpack8(rh_[1], v[2], v[3]);
;         if (m + NGW < M) { rh_[0] = *(const u32x4*)(H2 + (size_t)(m + NGW) * D + lane * 8); rh_[1] = *(const u32x4*)(H2 + (size_t)(m + NGW) * D + 512 + lane * 8); }
; #pragma unroll
;         for (int q = 0; q < 4; ++q) s += (v[q].x * v[q].x + v[q].y * v[q].y) + (v[q].z * v[q].z + v[q].w * v[q].w);
;         const float rstd = 1.0f / sqrtf(wave_sum(s) * (1.0f / D) + 1e-6f);
; #pragma unroll
;         for (int j = 0; j < 2; ++j) { float* o = out + (size_t)m * D + j * 512 + lane * 8; *(f32x4*)o = v[2 * j] * rstd * gv[2 * j]; *(f32x4*)(o + 4) = v[2 * j + 1] * rstd * gv[2 * j + 1]; }
;     }
.LBB0_1239:
	v_lshlrev_b32_e32 v45, 16, v29
	v_lshlrev_b32_e32 v44, 16, v28
	v_and_b32_e32 v29, 0xffff0000, v29
	v_and_b32_e32 v28, 0xffff0000, v28
	v_lshlrev_b32_e32 v48, 16, v24
	v_and_b32_e32 v49, 0xffff0000, v24
	v_lshlrev_b32_e32 v50, 16, v25
	v_and_b32_e32 v51, 0xffff0000, v25
	v_pk_mul_f32 v[24:25], v[28:29], v[28:29]
	v_lshlrev_b32_e32 v47, 16, v31
	v_lshlrev_b32_e32 v46, 16, v30
	v_and_b32_e32 v31, 0xffff0000, v31
	v_and_b32_e32 v30, 0xffff0000, v30
	v_pk_fma_f32 v[24:25], v[44:45], v[44:45], v[24:25]
	v_lshlrev_b32_e32 v52, 16, v26
	v_and_b32_e32 v62, 0xffff0000, v26
	v_lshlrev_b32_e32 v54, 16, v27
	v_and_b32_e32 v55, 0xffff0000, v27
	v_pk_add_f32 v[24:25], v[24:25], v[24:25] op_sel_hi:[0,1]
	v_pk_mul_f32 v[26:27], v[30:31], v[30:31]
	v_mul_f32_e32 v53, v48, v48
	v_pk_fma_f32 v[26:27], v[46:47], v[46:47], v[26:27]
	v_mul_f32_e32 v57, v49, v49
	v_mul_f32_e32 v24, v50, v50
	v_mov_b32_e32 v56, v52
	v_pk_add_f32 v[26:27], v[26:27], v[26:27] op_sel_hi:[0,1]
	v_pk_fma_f32 v[58:59], v[50:51], v[50:51], v[24:25] op_sel_hi:[1,1,0]
	v_pk_add_f32 v[56:57], v[52:53], v[56:57]
	v_mul_f32_e32 v58, v62, v62
	v_mul_f32_e32 v24, v54, v54
	v_mul_f32_e32 v26, v55, v55
	v_mul_f32_e32 v60, v52, v52
	v_mov_b32_e32 v61, v57
	v_pk_add_f32 v[56:57], v[60:61], v[58:59]
	v_pk_add_f32 v[24:25], v[24:25], v[26:27]
	v_lshl_add_u64 v[34:35], v[34:35], 0, s[6:7]
	v_pk_add_f32 v[24:25], v[56:57], v[24:25]
	s_nop 0
	v_add_f32_e32 v24, v24, v25
	s_nop 1
	v_mov_b32_dpp v25, v24 quad_perm:[1,0,3,2] row_mask:0xf bank_mask:0xf
	s_waitcnt lgkmcnt(0)
	v_add_f32_e32 v24, v24, v25
	s_nop 1
	v_mov_b32_dpp v25, v24 quad_perm:[2,3,0,1] row_mask:0xf bank_mask:0xf
	s_waitcnt lgkmcnt(0)
	v_add_f32_e32 v24, v24, v25
	s_nop 1
	v_mov_b32_dpp v25, v24 row_half_mirror row_mask:0xf bank_mask:0xf
	s_waitcnt lgkmcnt(0)
	v_add_f32_e32 v24, v24, v25
	s_nop 1
	v_mov_b32_dpp v25, v24 row_mirror row_mask:0xf bank_mask:0xf
	s_waitcnt lgkmcnt(0)
	v_add_f32_e32 v24, v24, v25
	v_mov_b32_e32 v25, v24
	s_nop 1
	v_permlane16_swap_b32_e32 v24, v25
	s_waitcnt lgkmcnt(0)
	v_add_f32_e32 v24, v24, v25
	v_mov_b32_e32 v25, v24
	s_nop 1
	v_permlane32_swap_b32_e32 v24, v25
	s_waitcnt lgkmcnt(0)
	v_add_f32_e32 v24, v24, v25
	v_fmamk_f32 v24, v24, 0x3a800000, v36
	v_mul_f32_e32 v25, 0x4f800000, v24
	v_cmp_gt_f32_e32 vcc, s3, v24
	s_nop 1
	v_cndmask_b32_e32 v24, v24, v25, vcc
	v_sqrt_f32_e32 v25, v24
	s_nop 0
	v_add_u32_e32 v26, -1, v25
	v_fma_f32 v27, -v26, v25, v24
	v_cmp_ge_f32_e64 s[0:1], 0, v27
	v_add_u32_e32 v27, 1, v25
	s_nop 0
	v_cndmask_b32_e64 v26, v25, v26, s[0:1]
	v_fma_f32 v25, -v27, v25, v24
	v_cmp_lt_f32_e64 s[0:1], 0, v25
	s_nop 1
	v_cndmask_b32_e64 v25, v26, v27, s[0:1]
	v_mul_f32_e32 v26, 0x37800000, v25
	v_cndmask_b32_e32 v25, v25, v26, vcc
	v_cmp_class_f32_e32 vcc, v24, v37
	s_nop 1
	v_cndmask_b32_e32 v24, v25, v24, vcc
	v_div_scale_f32 v25, s[0:1], v24, v24, 1.0
	v_rcp_f32_e32 v26, v25
	s_nop 0
	v_fma_f32 v27, -v25, v26, 1.0
	v_fmac_f32_e32 v26, v27, v26
	v_div_scale_f32 v27, vcc, 1.0, v24, 1.0
	v_mul_f32_e32 v53, v27, v26
	v_fma_f32 v56, -v25, v53, v27
	v_fmac_f32_e32 v53, v56, v26
	v_fma_f32 v25, -v25, v53, v27
	v_div_fmas_f32 v25, v25, v26, v53
	v_div_fixup_f32 v56, v25, v24, 1.0
	v_mov_b32_e32 v24, v44
	v_mov_b32_e32 v25, v28
	v_mov_b32_e32 v28, v45
	v_pk_mul_f32 v[24:25], v[56:57], v[24:25] op_sel_hi:[0,1]
	v_pk_mul_f32 v[26:27], v[56:57], v[28:29] op_sel_hi:[0,1]
	v_pk_mul_f32 v[26:27], v[6:7], v[26:27]
	v_pk_mul_f32 v[24:25], v[4:5], v[24:25]
	global_store_dwordx4 v[32:33], v[24:27], off
	v_mov_b32_e32 v53, v62
	s_andn2_b64 vcc, exec, s[10:11]
	v_mov_b32_e32 v24, v46
	v_mov_b32_e32 v25, v30
	v_mov_b32_e32 v30, v47
	v_pk_mul_f32 v[24:25], v[56:57], v[24:25] op_sel_hi:[0,1]
	v_pk_mul_f32 v[26:27], v[56:57], v[30:31] op_sel_hi:[0,1]
	v_pk_mul_f32 v[26:27], v[2:3], v[26:27]
	v_pk_mul_f32 v[24:25], v[0:1], v[24:25]
	global_store_dwordx4 v[32:33], v[24:27], off offset:16
	s_waitcnt vmcnt(3)
	v_mov_b64_e32 v[30:31], v[18:19]
	v_mov_b64_e32 v[28:29], v[16:17]
	v_pk_mul_f32 v[24:25], v[48:49], v[56:57] op_sel_hi:[1,0]
	v_pk_mul_f32 v[26:27], v[50:51], v[56:57] op_sel_hi:[1,0]
	v_pk_mul_f32 v[24:25], v[12:13], v[24:25]
	v_pk_mul_f32 v[26:27], v[14:15], v[26:27]
	global_store_dwordx4 v[32:33], v[24:27], off offset:2048
	s_nop 1
	v_pk_mul_f32 v[24:25], v[52:53], v[56:57] op_sel_hi:[1,0]
	v_pk_mul_f32 v[26:27], v[54:55], v[56:57] op_sel_hi:[1,0]
	v_pk_mul_f32 v[24:25], v[8:9], v[24:25]
	v_pk_mul_f32 v[26:27], v[10:11], v[26:27]
	global_store_dwordx4 v[32:33], v[24:27], off offset:2064
	v_lshl_add_u64 v[32:33], v[32:33], 0, s[4:5]
	s_waitcnt vmcnt(4)
	v_mov_b64_e32 v[26:27], v[22:23]
	v_mov_b64_e32 v[24:25], v[20:21]
	s_cbranch_vccz .LBB0_1242
